# LDS-crossbar shuffles (ds_bpermute + wait) replaced by DPP/readlane in the M1 wave-0 scan (wave max, lane-63 broadcast) and the MoBA gate dot reduction
# speedup vs baseline: 1.0156x; 1.0018x over previous
.LBB0_371:
	v_mov_b32_e32 v2, v69
	s_nop 0
	v_cmp_gt_u32_e64 s[0:1], 64, v2
	v_lshl_add_u32 v3, v2, 2, 0
	s_and_saveexec_b64 s[2:3], s[0:1]
	s_cbranch_execz .LBB0_374
	v_mul_f32_e64 v62, |v60|, s19
	v_exp_f32_e32 v84, v62
	v_max_f32_e32 v60, v60, v60
	v_min_f32_e32 v60, 0, v60
	v_add_f32_e32 v85, 1.0, v84
	v_add_f32_e32 v62, -1.0, v85
	v_sub_f32_e32 v63, v62, v85
	v_sub_f32_e32 v62, v84, v62
	v_add_f32_e32 v63, 1.0, v63
	v_add_f32_e32 v86, v62, v63
	v_frexp_mant_f32_e32 v87, v85
	v_cvt_f64_f32_e32 v[62:63], v85
	v_frexp_exp_i32_f64_e32 v62, v[62:63]
	v_cmp_gt_f32_e64 s[0:1], s30, v87
	s_nop 1
	v_subbrev_co_u32_e64 v62, s[0:1], 0, v62, s[0:1]
	v_sub_u32_e32 v63, 0, v62
	v_ldexp_f32 v85, v85, v63
	v_ldexp_f32 v63, v86, v63
	v_add_f32_e32 v86, -1.0, v85
	v_add_f32_e32 v89, 1.0, v85
	v_add_f32_e32 v87, 1.0, v86
	v_add_f32_e32 v90, -1.0, v89
	v_sub_f32_e32 v87, v85, v87
	v_sub_f32_e32 v85, v85, v90
	v_add_f32_e32 v87, v63, v87
	v_add_f32_e32 v63, v63, v85
	v_add_f32_e32 v85, v89, v63
	v_rcp_f32_e32 v90, v85
	v_add_f32_e32 v88, v86, v87
	v_sub_f32_e32 v86, v88, v86
	v_sub_f32_e32 v86, v87, v86
	v_sub_f32_e32 v87, v85, v89
	v_sub_f32_e32 v63, v63, v87
	v_mul_f32_e32 v87, v88, v90
	v_mul_f32_e32 v89, v85, v87
	v_fma_f32 v91, v87, v85, -v89
	v_fmac_f32_e32 v91, v87, v63
	v_add_f32_e32 v92, v89, v91
	v_sub_f32_e32 v93, v88, v92
	v_sub_f32_e32 v88, v88, v93
	v_sub_f32_e32 v89, v92, v89
	v_sub_f32_e32 v88, v88, v92
	v_add_f32_e32 v86, v86, v88
	v_sub_f32_e32 v88, v89, v91
	v_add_f32_e32 v86, v88, v86
	v_add_f32_e32 v88, v93, v86
	v_mul_f32_e32 v89, v90, v88
	v_mul_f32_e32 v91, v85, v89
	v_fma_f32 v85, v89, v85, -v91
	v_fmac_f32_e32 v85, v89, v63
	v_sub_f32_e32 v63, v93, v88
	v_add_f32_e32 v63, v86, v63
	v_add_f32_e32 v86, v91, v85
	v_sub_f32_e32 v92, v88, v86
	v_sub_f32_e32 v88, v88, v92
	v_sub_f32_e32 v91, v86, v91
	v_sub_f32_e32 v86, v88, v86
	v_add_f32_e32 v63, v63, v86
	v_sub_f32_e32 v85, v91, v85
	v_cvt_f32_i32_e32 v62, v62
	v_add_f32_e32 v63, v85, v63
	v_add_f32_e32 v85, v87, v89
	v_add_f32_e32 v63, v92, v63
	v_sub_f32_e32 v86, v85, v87
	v_mul_f32_e32 v63, v90, v63
	v_sub_f32_e32 v86, v89, v86
	v_add_f32_e32 v63, v86, v63
	v_mul_f32_e32 v89, 0x3f317218, v62
	v_add_f32_e32 v86, v85, v63
	v_fma_f32 v90, v62, s31, -v89
	v_mul_f32_e32 v87, v86, v86
	v_fmac_f32_e32 v90, 0xb102e308, v62
	v_sub_f32_e32 v62, v86, v85
	v_fmamk_f32 v88, v87, 0x3e9b6dac, v78
	v_sub_f32_e32 v62, v63, v62
	v_add_f32_e32 v63, v89, v90
	v_fmaak_f32 v88, v87, v88, 0x3f2aaada
	v_sub_f32_e32 v85, v63, v89
	v_ldexp_f32 v89, v86, 1
	v_mul_f32_e32 v86, v86, v87
	v_mul_f32_e32 v86, v86, v88
	v_add_f32_e32 v87, v89, v86
	v_sub_f32_e32 v88, v87, v89
	v_ldexp_f32 v62, v62, 1
	v_sub_f32_e32 v86, v86, v88
	v_add_f32_e32 v62, v62, v86
	v_add_f32_e32 v86, v87, v62
	v_sub_f32_e32 v87, v86, v87
	v_sub_f32_e32 v62, v62, v87
	v_add_f32_e32 v87, v63, v86
	v_sub_f32_e32 v88, v87, v63
	v_sub_f32_e32 v89, v87, v88
	v_sub_f32_e32 v85, v90, v85
	v_sub_f32_e32 v63, v63, v89
	v_sub_f32_e32 v86, v86, v88
	v_add_f32_e32 v63, v86, v63
	v_add_f32_e32 v86, v85, v62
	v_sub_f32_e32 v88, v86, v85
	v_sub_f32_e32 v89, v86, v88
	v_sub_f32_e32 v85, v85, v89
	v_sub_f32_e32 v62, v62, v88
	v_add_f32_e32 v63, v86, v63
	v_add_f32_e32 v62, v62, v85
	v_add_f32_e32 v85, v87, v63
	v_sub_f32_e32 v86, v85, v87
	v_sub_f32_e32 v63, v63, v86
	v_add_f32_e32 v62, v62, v63
	v_add_f32_e32 v62, v85, v62
	v_cmp_neq_f32_e64 s[0:1], s33, v84
	v_and_b32_e32 v63, 64, v82
	s_nop 0
	v_cndmask_b32_e64 v62, v79, v62, s[0:1]
	v_cmp_ngt_f32_e64 s[0:1], -1.0, v84
	s_nop 1
	v_cndmask_b32_e64 v62, v80, v62, s[0:1]
	v_cmp_neq_f32_e64 s[0:1], -1.0, v84
	s_nop 1
	v_cndmask_b32_e64 v62, v81, v62, s[0:1]
	v_cmp_lt_f32_e64 s[0:1], |v84|, s34
	s_nop 1
	v_cndmask_b32_e64 v62, v62, v84, s[0:1]
	v_sub_f32_e32 v60, v60, v62
	v_mov_b32_e32 v62, v0
	v_xor_b32_e32 v84, 2, v82
	v_add_f32_dpp v60, v60, v60 row_shr:1 row_mask:0xf bank_mask:0xf bound_ctrl:1
	s_nop 1
	v_add_f32_dpp v60, v60, v60 row_shr:2 row_mask:0xf bank_mask:0xf bound_ctrl:1
	s_nop 1
	v_add_f32_dpp v60, v60, v60 row_shr:4 row_mask:0xf bank_mask:0xf bound_ctrl:1
	s_nop 1
	v_add_f32_dpp v60, v60, v60 row_shr:8 row_mask:0xf bank_mask:0xf bound_ctrl:1
	s_nop 1
	v_mov_b32_dpp v62, v60 row_bcast:15 row_mask:0xa bank_mask:0xf
	v_add_f32_e32 v60, v60, v62
	v_mov_b32_e32 v62, v0
	s_nop 1
	v_mov_b32_dpp v62, v60 row_bcast:31 row_mask:0xc bank_mask:0xf
	v_add_f32_e32 v62, v60, v62
	s_nop 0
	v_readlane_b32 s0, v62, 63
	s_nop 1
	v_mov_b32_e32 v60, s0
	v_sub_f32_e32 v62, v60, v62
	v_add_f32_e32 v62, v61, v62
	v_max_f32_e32 v63, v62, v62
	s_nop 1
	v_max_f32_dpp v63, v63, v63 quad_perm:[1,0,3,2] row_mask:0xf bank_mask:0xf
	s_nop 1
	v_max_f32_dpp v63, v63, v63 quad_perm:[2,3,0,1] row_mask:0xf bank_mask:0xf
	s_nop 1
	v_max_f32_dpp v63, v63, v63 row_half_mirror row_mask:0xf bank_mask:0xf
	s_nop 1
	v_max_f32_dpp v63, v63, v63 row_mirror row_mask:0xf bank_mask:0xf
	s_nop 0
	v_readlane_b32 s0, v63, 0
	v_readlane_b32 s1, v63, 16
	s_nop 1
	v_mov_b32_e32 v61, s0
	v_max_f32_e32 v61, s1, v61
	v_readlane_b32 s0, v63, 32
	v_readlane_b32 s1, v63, 48
	s_nop 1
	v_max_f32_e32 v61, s0, v61
	v_max_f32_e32 v61, s1, v61
	v_cmp_eq_u32_e64 s[0:1], 0, v2
	v_sub_f32_e32 v62, v62, v61
	v_mul_f32_e32 v62, 0x3fb8aa3b, v62
	v_exp_f32_e32 v62, v62
	ds_write_b32 v3, v62 offset:36864
	s_and_b64 exec, exec, s[0:1]
	s_cbranch_execz .LBB0_374
	s_ashr_i32 s21, s20, 31
	s_lshl_b64 s[0:1], s[20:21], 2
	s_add_u32 s0, s38, s0
	s_addc_u32 s1, s39, s1
	global_store_dwordx2 v0, v[60:61], s[0:1]

.LBB0_517:
	ds_read_b128 v[44:47], v18
	ds_read_b128 v[48:51], v18 offset:16
	ds_read_b128 v[52:55], v18 offset:32
	ds_read_b128 v[56:59], v18 offset:48
	ds_read_b128 v[60:63], v18 offset:64
	s_waitcnt lgkmcnt(4)
	v_fma_f32 v64, v44, v21, 0
	v_fmac_f32_e32 v64, v45, v22
	v_fmac_f32_e32 v64, v46, v23
	v_fmac_f32_e32 v64, v47, v24
	s_waitcnt lgkmcnt(3)
	v_fmac_f32_e32 v64, v48, v25
	v_fmac_f32_e32 v64, v49, v26
	v_fmac_f32_e32 v64, v50, v27
	v_fmac_f32_e32 v64, v51, v28
	s_waitcnt lgkmcnt(2)
	v_fmac_f32_e32 v64, v52, v29
	v_fmac_f32_e32 v64, v53, v30
	v_fmac_f32_e32 v64, v54, v31
	v_fmac_f32_e32 v64, v55, v32
	s_waitcnt lgkmcnt(1)
	v_fmac_f32_e32 v64, v56, v33
	v_fmac_f32_e32 v64, v57, v34
	v_fmac_f32_e32 v64, v58, v35
	ds_read_b128 v[44:47], v18 offset:80
	ds_read_b128 v[48:51], v18 offset:96
	v_fmac_f32_e32 v64, v59, v36
	s_waitcnt lgkmcnt(2)
	v_fmac_f32_e32 v64, v60, v38
	v_fmac_f32_e32 v64, v61, v39
	v_fmac_f32_e32 v64, v62, v40
	v_fmac_f32_e32 v64, v63, v41
	s_waitcnt lgkmcnt(1)
	v_pk_mul_f32 v[44:45], v[44:45], v[2:3]
	s_waitcnt lgkmcnt(0)
	v_pk_mul_f32 v[48:49], v[48:49], v[8:9]
	v_add_f32_e32 v44, v64, v44
	v_add_f32_e32 v52, v44, v45
	v_pk_mul_f32 v[44:45], v[46:47], v[6:7]
	s_nop 0
	v_add_f32_e32 v44, v52, v44
	v_add_f32_e32 v52, v44, v45
	ds_read_b128 v[44:47], v18 offset:112
	v_add_f32_e32 v48, v52, v48
	v_add_f32_e32 v52, v48, v49
	v_pk_mul_f32 v[48:49], v[50:51], v[10:11]
	s_waitcnt lgkmcnt(0)
	v_pk_mul_f32 v[44:45], v[44:45], v[12:13]
	v_add_f32_e32 v48, v52, v48
	v_add_f32_e32 v48, v48, v49
	v_add_f32_e32 v44, v48, v44
	v_add_f32_e32 v48, v44, v45
	v_pk_mul_f32 v[44:45], v[46:47], v[14:15]
	s_nop 0
	v_add_f32_e32 v44, v48, v44
	v_add_f32_e32 v44, v44, v45
	s_nop 1
	v_add_f32_dpp v44, v44, v44 quad_perm:[1,0,3,2] row_mask:0xf bank_mask:0xf
	v_cmp_ngt_f32_e32 vcc, v44, v43
	v_mov_b32_e32 v45, s4
	s_and_saveexec_b64 s[2:3], vcc
	s_cbranch_execz .LBB0_523
	v_cmp_ngt_f32_e32 vcc, v44, v19
	v_mov_b32_e32 v46, s4
	s_and_saveexec_b64 s[8:9], vcc
	s_cbranch_execz .LBB0_522
	v_cmp_gt_f32_e32 vcc, v44, v42
	s_and_saveexec_b64 s[10:11], vcc
	v_mov_b32_e32 v37, s4
	v_mov_b32_e32 v42, v44
	s_or_b64 exec, exec, s[10:11]
	v_mov_b32_e32 v46, v5
	v_mov_b32_e32 v44, v19
	v_mov_b32_e32 v19, v42
	v_mov_b32_e32 v5, v37
